# one static s_setprio 1 at kernel entry for the second half of the grid (blocks 256..511, the later arrival on each CU)
# baseline (speedup 1.0000x reference)
_Z15yoco_megakernel5KArgsii:
	s_load_dwordx2 s[34:35], s[0:1], 0xf0
	v_and_b32_e32 v166, 0x3ff, v0
	s_mov_b32 s85, s2
	s_cmp_lt_u32 s85, 0x100
	s_cbranch_scc1 .Lprio_lo
	s_setprio 1
.Lprio_lo:
	v_cmp_gt_u32_e32 vcc, 4, v166
	s_and_saveexec_b64 s[4:5], vcc
	v_mov_b32_e32 v1, 0x12000
	v_lshl_or_b32 v1, v166, 2, v1
	v_mov_b32_e32 v2, 0
	ds_write_b32 v1, v2
	s_or_b64 exec, exec, s[4:5]
	s_load_dwordx16 s[52:67], s[0:1], 0x0
	s_waitcnt lgkmcnt(0)
	s_barrier
	s_getreg_b32 s2, hwreg(HW_REG_XCC_ID, 0, 4)
	s_and_b32 s84, s2, 15
	v_cmp_eq_u32_e64 s[2:3], 0, v166
	s_mov_b64 s[4:5], exec
	s_nop 0
	v_writelane_b32 v231, s2, 0
	s_nop 1
	v_writelane_b32 v231, s3, 1
	s_and_b64 s[2:3], s[4:5], s[2:3]
	s_mov_b64 exec, s[2:3]
	s_cbranch_execz .LBB0_5
	s_mov_b64 s[6:7], exec
	v_mbcnt_lo_u32_b32 v1, s6, 0
	v_mbcnt_hi_u32_b32 v1, s7, v1
	v_cmp_eq_u32_e32 vcc, 0, v1
	s_and_b64 s[2:3], exec, vcc
	s_mov_b64 exec, s[2:3]
	s_cbranch_execz .LBB0_5
	s_lshl_b32 s2, s84, 8
	s_bcnt1_i32_b64 s3, s[6:7]
	v_mov_b32_e32 v1, s2
	v_mov_b32_e32 v2, s3
	global_atomic_add v1, v2, s[34:35] offset:1024
